# MIX item: epilogue operand loads (U rows, gains, biases) hoisted to the item top sharing the V-tile DMA round trip; two ssp load batches merged
# baseline (speedup 1.0000x reference)
.Lmy_mix0_wdone:
	s_waitcnt vmcnt(0)
	s_waitcnt lgkmcnt(0)
	s_barrier
	s_lshl_b32 s8, s1, 1
	s_mov_b32 s9, s5
	v_or_b32_e32 v94, s91, v65
	v_or_b32_e32 v79, s4, v65
	v_ashrrev_i32_e32 v95, 31, v94
	v_lshlrev_b32_e32 v79, 2, v79
	v_lshlrev_b64 v[94:95], 12, v[94:95]
	s_add_i32 s90, s90, s0
	s_add_i32 s85, s85, s92
	ds_read_b64_tr_b16 v[180:181], v116
	ds_read_b64_tr_b16 v[182:183], v116 offset:2048
	ds_read_b128 v[132:135], v117
	ds_read_b128 v[136:139], v117 offset:8192
	ds_read_b128 v[140:143], v117 offset:16384
	ds_read_b128 v[144:147], v117 offset:24576
	ds_read_b64_tr_b16 v[184:185], v116 offset:8192
	ds_read_b64_tr_b16 v[186:187], v116 offset:10240
	ds_read_b128 v[148:151], v118
	ds_read_b128 v[152:155], v118 offset:8192
	ds_read_b128 v[156:159], v118 offset:16384
	ds_read_b128 v[160:163], v118 offset:24576
	s_waitcnt lgkmcnt(6)
	ds_read_b64_tr_b16 v[188:189], v116 offset:16384
	ds_read_b64_tr_b16 v[190:191], v116 offset:18432
	ds_read_b128 v[168:171], v119 offset:8192
	ds_read_b128 v[172:175], v119 offset:16384
	ds_read_b128 v[176:179], v119 offset:24576
	v_mfma_f32_32x32x16_bf16 v[48:63], v[180:183], v[132:135], 0
	v_mfma_f32_32x32x16_bf16 v[32:47], v[180:183], v[136:139], 0
	v_mfma_f32_32x32x16_bf16 v[16:31], v[180:183], v[140:143], 0
	v_mfma_f32_32x32x16_bf16 v[0:15], v[180:183], v[144:147], 0
	s_waitcnt lgkmcnt(5)
	ds_read_b64_tr_b16 v[180:181], v116 offset:24576
	ds_read_b64_tr_b16 v[182:183], v116 offset:26624
	ds_read_b128 v[136:139], v120 offset:8192
	ds_read_b128 v[140:143], v120 offset:16384
	ds_read_b128 v[144:147], v120 offset:24576
	v_mfma_f32_32x32x16_bf16 v[48:63], v[184:187], v[148:151], v[48:63]
	v_mfma_f32_32x32x16_bf16 v[32:47], v[184:187], v[152:155], v[32:47]
	v_mfma_f32_32x32x16_bf16 v[16:31], v[184:187], v[156:159], v[16:31]
	v_mfma_f32_32x32x16_bf16 v[0:15], v[184:187], v[160:163], v[0:15]
	s_waitcnt lgkmcnt(5)
	ds_read_b64_tr_b16 v[184:185], v116 offset:32768
	ds_read_b64_tr_b16 v[186:187], v116 offset:34816
	ds_read_b128 v[156:159], v121 offset:16384
	ds_read_b128 v[160:163], v121 offset:24576
	v_mfma_f32_32x32x16_bf16 v[32:47], v[188:191], v[168:171], v[32:47]
	v_mfma_f32_32x32x16_bf16 v[16:31], v[188:191], v[172:175], v[16:31]
	v_mfma_f32_32x32x16_bf16 v[0:15], v[188:191], v[176:179], v[0:15]
	s_waitcnt lgkmcnt(4)
	ds_read_b64_tr_b16 v[188:189], v116 offset:40960
	ds_read_b64_tr_b16 v[190:191], v116 offset:43008
	ds_read_b128 v[172:175], v122 offset:16384
	ds_read_b128 v[176:179], v122 offset:24576
	v_mfma_f32_32x32x16_bf16 v[32:47], v[180:183], v[136:139], v[32:47]
	v_mfma_f32_32x32x16_bf16 v[16:31], v[180:183], v[140:143], v[16:31]
	v_mfma_f32_32x32x16_bf16 v[0:15], v[180:183], v[144:147], v[0:15]
	s_waitcnt lgkmcnt(4)
	ds_read_b64_tr_b16 v[180:181], v116 offset:49152
	ds_read_b64_tr_b16 v[182:183], v116 offset:51200
	ds_read_b128 v[144:147], v123 offset:24576
	v_mfma_f32_32x32x16_bf16 v[16:31], v[184:187], v[156:159], v[16:31]
	v_mfma_f32_32x32x16_bf16 v[0:15], v[184:187], v[160:163], v[0:15]
	s_waitcnt lgkmcnt(3)
	ds_read_b64_tr_b16 v[184:185], v116 offset:57344
	ds_read_b64_tr_b16 v[186:187], v116 offset:59392
	ds_read_b128 v[160:163], v124 offset:24576
	v_mfma_f32_32x32x16_bf16 v[16:31], v[188:191], v[172:175], v[16:31]
	v_mfma_f32_32x32x16_bf16 v[0:15], v[188:191], v[176:179], v[0:15]
	s_waitcnt lgkmcnt(3)
	v_mfma_f32_32x32x16_bf16 v[0:15], v[180:183], v[144:147], v[0:15]
	s_waitcnt lgkmcnt(0)
	v_mfma_f32_32x32x16_bf16 v[0:15], v[184:187], v[160:163], v[0:15]
	v_lshl_add_u64 v[92:93], v[72:73], 0, s[8:9]
	s_lshl_b32 s8, s1, 2
	v_lshl_add_u64 v[90:91], v[74:75], 0, s[8:9]
	v_lshl_add_u64 v[94:95], v[92:93], 0, v[94:95]
	s_cmpk_gt_i32 s90, 0x3ff
	s_waitcnt vmcnt(0)
	v_fma_f32 v48, v48, v204, v200
	v_lshlrev_b32_e32 v132, 16, v220
	v_and_b32_e32 v133, 0xffff0000, v220
	v_fma_f32 v49, v49, v205, v200
	v_mul_f32_e32 v48, v48, v132
	v_mul_f32_e32 v49, v49, v133
	v_lshlrev_b32_e32 v134, 16, v221
	v_and_b32_e32 v135, 0xffff0000, v221
	v_fma_f32 v50, v50, v206, v200
	v_fma_f32 v51, v51, v207, v200
	v_mul_f32_e32 v50, v50, v134
	v_mul_f32_e32 v51, v51, v135
	v_cvt_pk_bf16_f32 v48, v48, v49
	v_cvt_pk_bf16_f32 v49, v50, v51
	global_store_dwordx2 v[192:193], v[48:49], off
	v_fma_f32 v52, v52, v208, v200
	v_lshlrev_b32_e32 v132, 16, v222
	v_and_b32_e32 v133, 0xffff0000, v222
	v_fma_f32 v53, v53, v209, v200
	v_mul_f32_e32 v52, v52, v132
	v_mul_f32_e32 v53, v53, v133
	v_lshlrev_b32_e32 v134, 16, v223
	v_and_b32_e32 v135, 0xffff0000, v223
	v_fma_f32 v54, v54, v210, v200
	v_fma_f32 v55, v55, v211, v200
	v_mul_f32_e32 v54, v54, v134
	v_mul_f32_e32 v55, v55, v135
	v_cvt_pk_bf16_f32 v52, v52, v53
	v_cvt_pk_bf16_f32 v53, v54, v55
	global_store_dwordx2 v[192:193], v[52:53], off offset:16
	v_fma_f32 v56, v56, v212, v200
	v_lshlrev_b32_e32 v132, 16, v224
	v_and_b32_e32 v133, 0xffff0000, v224
	v_fma_f32 v57, v57, v213, v200
	v_mul_f32_e32 v56, v56, v132
	v_mul_f32_e32 v57, v57, v133
	v_lshlrev_b32_e32 v134, 16, v225
	v_and_b32_e32 v135, 0xffff0000, v225
	v_fma_f32 v58, v58, v214, v200
	v_fma_f32 v59, v59, v215, v200
	v_mul_f32_e32 v58, v58, v134
	v_mul_f32_e32 v59, v59, v135
	v_cvt_pk_bf16_f32 v56, v56, v57
	v_cvt_pk_bf16_f32 v57, v58, v59
	global_store_dwordx2 v[192:193], v[56:57], off offset:32
	v_fma_f32 v60, v60, v216, v200
	v_lshlrev_b32_e32 v132, 16, v226
	v_and_b32_e32 v133, 0xffff0000, v226
	v_fma_f32 v61, v61, v217, v200
	v_mul_f32_e32 v60, v60, v132
	v_mul_f32_e32 v61, v61, v133
	v_lshlrev_b32_e32 v134, 16, v227
	v_and_b32_e32 v135, 0xffff0000, v227
	v_fma_f32 v62, v62, v218, v200
	v_fma_f32 v63, v63, v219, v200
	v_mul_f32_e32 v62, v62, v134
	v_mul_f32_e32 v63, v63, v135
	v_cvt_pk_bf16_f32 v60, v60, v61
	v_cvt_pk_bf16_f32 v61, v62, v63
	global_store_dwordx2 v[192:193], v[60:61], off offset:48
	v_fma_f32 v32, v32, v204, v201
	v_lshlrev_b32_e32 v132, 16, v228
	v_and_b32_e32 v133, 0xffff0000, v228
	v_fma_f32 v33, v33, v205, v201
	v_mul_f32_e32 v32, v32, v132
	v_mul_f32_e32 v33, v33, v133
	v_lshlrev_b32_e32 v134, 16, v229
	v_and_b32_e32 v135, 0xffff0000, v229
	v_fma_f32 v34, v34, v206, v201
	v_fma_f32 v35, v35, v207, v201
	v_mul_f32_e32 v34, v34, v134
	v_mul_f32_e32 v35, v35, v135
	v_cvt_pk_bf16_f32 v32, v32, v33
	v_cvt_pk_bf16_f32 v33, v34, v35
	global_store_dwordx2 v[194:195], v[32:33], off
	v_fma_f32 v36, v36, v208, v201
	v_lshlrev_b32_e32 v132, 16, v230
	v_and_b32_e32 v133, 0xffff0000, v230
	v_fma_f32 v37, v37, v209, v201
	v_mul_f32_e32 v36, v36, v132
	v_mul_f32_e32 v37, v37, v133
	v_lshlrev_b32_e32 v134, 16, v231
	v_and_b32_e32 v135, 0xffff0000, v231
	v_fma_f32 v38, v38, v210, v201
	v_fma_f32 v39, v39, v211, v201
	v_mul_f32_e32 v38, v38, v134
	v_mul_f32_e32 v39, v39, v135
	v_cvt_pk_bf16_f32 v36, v36, v37
	v_cvt_pk_bf16_f32 v37, v38, v39
	global_store_dwordx2 v[194:195], v[36:37], off offset:16
	v_fma_f32 v40, v40, v212, v201
	v_lshlrev_b32_e32 v132, 16, v232
	v_and_b32_e32 v133, 0xffff0000, v232
	v_fma_f32 v41, v41, v213, v201
	v_mul_f32_e32 v40, v40, v132
	v_mul_f32_e32 v41, v41, v133
	v_lshlrev_b32_e32 v134, 16, v233
	v_and_b32_e32 v135, 0xffff0000, v233
	v_fma_f32 v42, v42, v214, v201
	v_fma_f32 v43, v43, v215, v201
	v_mul_f32_e32 v42, v42, v134
	v_mul_f32_e32 v43, v43, v135
	v_cvt_pk_bf16_f32 v40, v40, v41
	v_cvt_pk_bf16_f32 v41, v42, v43
	global_store_dwordx2 v[194:195], v[40:41], off offset:32
	v_fma_f32 v44, v44, v216, v201
	v_lshlrev_b32_e32 v132, 16, v234
	v_and_b32_e32 v133, 0xffff0000, v234
	v_fma_f32 v45, v45, v217, v201
	v_mul_f32_e32 v44, v44, v132
	v_mul_f32_e32 v45, v45, v133
	v_lshlrev_b32_e32 v134, 16, v235
	v_and_b32_e32 v135, 0xffff0000, v235
	v_fma_f32 v46, v46, v218, v201
	v_fma_f32 v47, v47, v219, v201
	v_mul_f32_e32 v46, v46, v134
	v_mul_f32_e32 v47, v47, v135
	v_cvt_pk_bf16_f32 v44, v44, v45
	v_cvt_pk_bf16_f32 v45, v46, v47
	global_store_dwordx2 v[194:195], v[44:45], off offset:48
	v_fma_f32 v16, v16, v204, v202
	v_lshlrev_b32_e32 v132, 16, v236
	v_and_b32_e32 v133, 0xffff0000, v236
	v_fma_f32 v17, v17, v205, v202
	v_mul_f32_e32 v16, v16, v132
	v_mul_f32_e32 v17, v17, v133
	v_lshlrev_b32_e32 v134, 16, v237
	v_and_b32_e32 v135, 0xffff0000, v237
	v_fma_f32 v18, v18, v206, v202
	v_fma_f32 v19, v19, v207, v202
	v_mul_f32_e32 v18, v18, v134
	v_mul_f32_e32 v19, v19, v135
	v_cvt_pk_bf16_f32 v16, v16, v17
	v_cvt_pk_bf16_f32 v17, v18, v19
	global_store_dwordx2 v[196:197], v[16:17], off
	v_fma_f32 v20, v20, v208, v202
	v_lshlrev_b32_e32 v132, 16, v238
	v_and_b32_e32 v133, 0xffff0000, v238
	v_fma_f32 v21, v21, v209, v202
	v_mul_f32_e32 v20, v20, v132
	v_mul_f32_e32 v21, v21, v133
	v_lshlrev_b32_e32 v134, 16, v239
	v_and_b32_e32 v135, 0xffff0000, v239
	v_fma_f32 v22, v22, v210, v202
	v_fma_f32 v23, v23, v211, v202
	v_mul_f32_e32 v22, v22, v134
	v_mul_f32_e32 v23, v23, v135
	v_cvt_pk_bf16_f32 v20, v20, v21
	v_cvt_pk_bf16_f32 v21, v22, v23
	global_store_dwordx2 v[196:197], v[20:21], off offset:16
	v_fma_f32 v24, v24, v212, v202
	v_lshlrev_b32_e32 v132, 16, v240
	v_and_b32_e32 v133, 0xffff0000, v240
	v_fma_f32 v25, v25, v213, v202
	v_mul_f32_e32 v24, v24, v132
	v_mul_f32_e32 v25, v25, v133
	v_lshlrev_b32_e32 v134, 16, v241
	v_and_b32_e32 v135, 0xffff0000, v241
	v_fma_f32 v26, v26, v214, v202
	v_fma_f32 v27, v27, v215, v202
	v_mul_f32_e32 v26, v26, v134
	v_mul_f32_e32 v27, v27, v135
	v_cvt_pk_bf16_f32 v24, v24, v25
	v_cvt_pk_bf16_f32 v25, v26, v27
	global_store_dwordx2 v[196:197], v[24:25], off offset:32
	v_fma_f32 v28, v28, v216, v202
	v_lshlrev_b32_e32 v132, 16, v242
	v_and_b32_e32 v133, 0xffff0000, v242
	v_fma_f32 v29, v29, v217, v202
	v_mul_f32_e32 v28, v28, v132
	v_mul_f32_e32 v29, v29, v133
	v_lshlrev_b32_e32 v134, 16, v243
	v_and_b32_e32 v135, 0xffff0000, v243
	v_fma_f32 v30, v30, v218, v202
	v_fma_f32 v31, v31, v219, v202
	v_mul_f32_e32 v30, v30, v134
	v_mul_f32_e32 v31, v31, v135
	v_cvt_pk_bf16_f32 v28, v28, v29
	v_cvt_pk_bf16_f32 v29, v30, v31
	global_store_dwordx2 v[196:197], v[28:29], off offset:48
	v_fma_f32 v0, v0, v204, v203
	v_lshlrev_b32_e32 v132, 16, v244
	v_and_b32_e32 v133, 0xffff0000, v244
	v_fma_f32 v1, v1, v205, v203
	v_mul_f32_e32 v0, v0, v132
	v_mul_f32_e32 v1, v1, v133
	v_lshlrev_b32_e32 v134, 16, v245
	v_and_b32_e32 v135, 0xffff0000, v245
	v_fma_f32 v2, v2, v206, v203
	v_fma_f32 v3, v3, v207, v203
	v_mul_f32_e32 v2, v2, v134
	v_mul_f32_e32 v3, v3, v135
	v_cvt_pk_bf16_f32 v0, v0, v1
	v_cvt_pk_bf16_f32 v1, v2, v3
	global_store_dwordx2 v[198:199], v[0:1], off
	v_fma_f32 v4, v4, v208, v203
	v_lshlrev_b32_e32 v132, 16, v246
	v_and_b32_e32 v133, 0xffff0000, v246
	v_fma_f32 v5, v5, v209, v203
	v_mul_f32_e32 v4, v4, v132
	v_mul_f32_e32 v5, v5, v133
	v_lshlrev_b32_e32 v134, 16, v247
	v_and_b32_e32 v135, 0xffff0000, v247
	v_fma_f32 v6, v6, v210, v203
	v_fma_f32 v7, v7, v211, v203
	v_mul_f32_e32 v6, v6, v134
	v_mul_f32_e32 v7, v7, v135
	v_cvt_pk_bf16_f32 v4, v4, v5
	v_cvt_pk_bf16_f32 v5, v6, v7
	global_store_dwordx2 v[198:199], v[4:5], off offset:16
	v_fma_f32 v8, v8, v212, v203
	v_lshlrev_b32_e32 v132, 16, v248
	v_and_b32_e32 v133, 0xffff0000, v248
	v_fma_f32 v9, v9, v213, v203
	v_mul_f32_e32 v8, v8, v132
	v_mul_f32_e32 v9, v9, v133
	v_lshlrev_b32_e32 v134, 16, v249
	v_and_b32_e32 v135, 0xffff0000, v249
	v_fma_f32 v10, v10, v214, v203
	v_fma_f32 v11, v11, v215, v203
	v_mul_f32_e32 v10, v10, v134
	v_mul_f32_e32 v11, v11, v135
	v_cvt_pk_bf16_f32 v8, v8, v9
	v_cvt_pk_bf16_f32 v9, v10, v11
	global_store_dwordx2 v[198:199], v[8:9], off offset:32
	v_fma_f32 v12, v12, v216, v203
	v_lshlrev_b32_e32 v132, 16, v250
	v_and_b32_e32 v133, 0xffff0000, v250
	v_fma_f32 v13, v13, v217, v203
	v_mul_f32_e32 v12, v12, v132
	v_mul_f32_e32 v13, v13, v133
	v_lshlrev_b32_e32 v134, 16, v251
	v_and_b32_e32 v135, 0xffff0000, v251
	v_fma_f32 v14, v14, v218, v203
	v_fma_f32 v15, v15, v219, v203
	v_mul_f32_e32 v14, v14, v134
	v_mul_f32_e32 v15, v15, v135
	v_cvt_pk_bf16_f32 v12, v12, v13
	v_cvt_pk_bf16_f32 v13, v14, v15
	global_store_dwordx2 v[198:199], v[12:13], off offset:48
	s_barrier
	s_cbranch_scc1 .LBB0_305
.LBB0_239:
	s_and_b32 s1, s90, 7
	s_and_b32 s91, s85, 0xffffff80
	s_lshl_b32 s2, s1, 9
	v_readlane_b32 s4, v255, 35
	v_add_u32_e32 v0, s91, v100
	s_add_u32 s8, s4, s2
	v_readlane_b32 s2, v255, 37
	v_ashrrev_i32_e32 v1, 31, v0
	s_addc_u32 s9, s2, 0
	v_lshlrev_b64 v[0:1], 12, v[0:1]
	v_lshl_add_u64 v[0:1], s[8:9], 0, v[0:1]
	s_mov_b32 m0, s93
	v_lshl_add_u64 v[0:1], v[0:1], 0, v[76:77]
	global_load_lds_dwordx4 v[0:1], off
	v_add_u32_e32 v0, s91, v101
	v_ashrrev_i32_e32 v1, 31, v0
	v_lshlrev_b64 v[0:1], 12, v[0:1]
	v_lshl_add_u64 v[0:1], s[8:9], 0, v[0:1]
	v_lshl_add_u64 v[0:1], v[0:1], 0, v[66:67]
	s_mov_b32 m0, s94
	v_mov_b32_e32 v79, v67
	global_load_lds_dwordx4 v[0:1], off
	v_add_u32_e32 v0, s91, v102
	v_ashrrev_i32_e32 v1, 31, v0
	v_lshlrev_b64 v[0:1], 12, v[0:1]
	v_lshl_add_u64 v[0:1], s[8:9], 0, v[0:1]
	v_lshl_add_u64 v[0:1], v[0:1], 0, v[78:79]
	s_mov_b32 m0, s95
	v_mov_b32_e32 v81, v67
	global_load_lds_dwordx4 v[0:1], off
	v_add_u32_e32 v0, s91, v103
	v_ashrrev_i32_e32 v1, 31, v0
	v_lshlrev_b64 v[0:1], 12, v[0:1]
	v_lshl_add_u64 v[0:1], s[8:9], 0, v[0:1]
	v_lshl_add_u64 v[0:1], v[0:1], 0, v[80:81]
	s_mov_b32 m0, s78
	v_mov_b32_e32 v83, v67
	global_load_lds_dwordx4 v[0:1], off
	v_add_u32_e32 v0, s91, v104
	v_ashrrev_i32_e32 v1, 31, v0
	v_lshlrev_b64 v[0:1], 12, v[0:1]
	v_lshl_add_u64 v[0:1], s[8:9], 0, v[0:1]
	v_lshl_add_u64 v[0:1], v[0:1], 0, v[82:83]
	s_mov_b32 m0, s79
	v_mov_b32_e32 v85, v67
	global_load_lds_dwordx4 v[0:1], off
	v_add_u32_e32 v0, s91, v105
	v_ashrrev_i32_e32 v1, 31, v0
	v_lshlrev_b64 v[0:1], 12, v[0:1]
	v_lshl_add_u64 v[0:1], s[8:9], 0, v[0:1]
	v_lshl_add_u64 v[0:1], v[0:1], 0, v[84:85]
	s_mov_b32 m0, s3
	v_mov_b32_e32 v87, v67
	global_load_lds_dwordx4 v[0:1], off
	v_add_u32_e32 v0, s91, v106
	v_ashrrev_i32_e32 v1, 31, v0
	v_lshlrev_b64 v[0:1], 12, v[0:1]
	v_lshl_add_u64 v[0:1], s[8:9], 0, v[0:1]
	v_lshl_add_u64 v[0:1], v[0:1], 0, v[86:87]
	s_mov_b32 m0, s76
	v_mov_b32_e32 v89, v67
	global_load_lds_dwordx4 v[0:1], off
	v_add_u32_e32 v0, s91, v107
	v_ashrrev_i32_e32 v1, 31, v0
	v_lshlrev_b64 v[0:1], 12, v[0:1]
	v_lshl_add_u64 v[0:1], s[8:9], 0, v[0:1]
	v_lshl_add_u64 v[0:1], v[0:1], 0, v[88:89]
	s_mov_b32 m0, s77
	s_nop 0
	global_load_lds_dwordx4 v[0:1], off
	s_lshl_b32 s98, s1, 9
	s_mov_b32 s99, 0
	v_lshl_add_u64 v[2:3], v[72:73], 0, s[98:99]
	s_lshl_b32 s98, s1, 10
	v_lshl_add_u64 v[4:5], v[74:75], 0, s[98:99]
	s_lshl_b32 s98, s1, 7
	v_or_b32_e32 v6, s91, v65
	v_ashrrev_i32_e32 v7, 31, v6
	v_lshlrev_b64 v[6:7], 12, v[6:7]
	v_lshl_add_u64 v[192:193], v[2:3], 0, v[6:7]
	v_or_b32_e32 v6, s98, v65
	v_lshlrev_b32_e32 v6, 2, v6
	global_load_dword v200, v6, s[96:97]
	global_load_dwordx2 v[220:221], v[192:193], off
	global_load_dwordx2 v[222:223], v[192:193], off offset:16
	global_load_dwordx2 v[224:225], v[192:193], off offset:32
	global_load_dwordx2 v[226:227], v[192:193], off offset:48
	v_or_b32_e32 v6, s91, v108
	v_ashrrev_i32_e32 v7, 31, v6
	v_lshlrev_b64 v[6:7], 12, v[6:7]
	v_lshl_add_u64 v[194:195], v[2:3], 0, v[6:7]
	v_or_b32_e32 v6, s98, v108
	v_lshlrev_b32_e32 v6, 2, v6
	global_load_dword v201, v6, s[96:97]
	global_load_dwordx2 v[228:229], v[194:195], off
	global_load_dwordx2 v[230:231], v[194:195], off offset:16
	global_load_dwordx2 v[232:233], v[194:195], off offset:32
	global_load_dwordx2 v[234:235], v[194:195], off offset:48
	v_or_b32_e32 v6, s91, v109
	v_ashrrev_i32_e32 v7, 31, v6
	v_lshlrev_b64 v[6:7], 12, v[6:7]
	v_lshl_add_u64 v[196:197], v[2:3], 0, v[6:7]
	v_or_b32_e32 v6, s98, v109
	v_lshlrev_b32_e32 v6, 2, v6
	global_load_dword v202, v6, s[96:97]
	global_load_dwordx2 v[236:237], v[196:197], off
	global_load_dwordx2 v[238:239], v[196:197], off offset:16
	global_load_dwordx2 v[240:241], v[196:197], off offset:32
	global_load_dwordx2 v[242:243], v[196:197], off offset:48
	v_or_b32_e32 v6, s91, v110
	v_ashrrev_i32_e32 v7, 31, v6
	v_lshlrev_b64 v[6:7], 12, v[6:7]
	v_lshl_add_u64 v[198:199], v[2:3], 0, v[6:7]
	v_or_b32_e32 v6, s98, v110
	v_lshlrev_b32_e32 v6, 2, v6
	global_load_dword v203, v6, s[96:97]
	global_load_dwordx2 v[244:245], v[198:199], off
	global_load_dwordx2 v[246:247], v[198:199], off offset:16
	global_load_dwordx2 v[248:249], v[198:199], off offset:32
	global_load_dwordx2 v[250:251], v[198:199], off offset:48
	global_load_dwordx4 v[204:207], v[4:5], off
	global_load_dwordx4 v[208:211], v[4:5], off offset:32
	global_load_dwordx4 v[212:215], v[4:5], off offset:64
	global_load_dwordx4 v[216:219], v[4:5], off offset:96
	s_and_saveexec_b64 s[8:9], vcc
	s_cbranch_execz .LBB0_241
	v_add_u32_e32 v0, s91, v97
	v_ashrrev_i32_e32 v1, 31, v0
	v_readlane_b32 s74, v255, 22
	v_lshlrev_b64 v[0:1], 7, v[0:1]
	v_readlane_b32 s75, v255, 23
	s_mov_b32 s2, 0x800000
	s_nop 0
	v_lshl_add_u64 v[16:17], s[74:75], 0, v[0:1]
	global_load_dwordx4 v[0:3], v[16:17], off offset:48
	global_load_dwordx4 v[4:7], v[16:17], off offset:32
	global_load_dwordx4 v[8:11], v[16:17], off
	global_load_dwordx4 v[12:15], v[16:17], off offset:16
	global_load_dwordx4 v[32:35], v[16:17], off offset:112
	global_load_dwordx4 v[36:39], v[16:17], off offset:96
	global_load_dwordx4 v[40:43], v[16:17], off offset:80
	global_load_dwordx4 v[44:47], v[16:17], off offset:64
	s_waitcnt vmcnt(0)
	v_add_f32_e32 v22, v0, v1
	v_add_f32_e32 v24, v2, v3
	v_mov_b32_e32 v18, v8
	v_mov_b32_e32 v19, v12
	v_mov_b32_e32 v12, v9
	v_pk_add_f32 v[8:9], v[18:19], v[12:13]
	v_mov_b32_e32 v12, v10
	v_mov_b32_e32 v13, v14
	v_mov_b32_e32 v14, v11
	v_pk_add_f32 v[10:11], v[12:13], v[14:15]
	s_nop 0
	v_pk_add_f32 v[8:9], v[8:9], v[10:11]
	s_nop 0
	v_add_f32_e32 v8, 0, v8
	v_add_f32_e32 v18, v8, v9
	v_mov_b32_e32 v8, v5
	v_mov_b32_e32 v9, v6
	v_mov_b32_e32 v5, v7
	v_pk_add_f32 v[4:5], v[8:9], v[4:5]
	s_nop 0
	v_pk_add_f32 v[20:21], v[4:5], v[4:5] op_sel:[0,1] op_sel_hi:[1,0]
	v_add_f32_e32 v36, v36, v37
	v_add_f32_e32 v38, v38, v39
	v_mov_b32_e32 v19, v44
	v_mov_b32_e32 v21, v45
	v_mov_b32_e32 v23, v46
	v_mov_b32_e32 v25, v47
	v_pk_add_f32 v[44:45], v[18:19], v[20:21]
	v_pk_add_f32 v[46:47], v[22:23], v[24:25]
	v_mov_b32_e32 v37, v34
	v_pk_add_f32 v[44:45], v[44:45], v[46:47]
	v_mov_b32_e32 v46, v41
	v_mov_b32_e32 v47, v42
	v_mov_b32_e32 v41, v43
	v_pk_add_f32 v[40:41], v[46:47], v[40:41]
	v_pk_add_f32 v[44:45], v[44:45], v[44:45] op_sel:[0,1] op_sel_hi:[1,0]
	v_pk_add_f32 v[40:41], v[40:41], v[40:41] op_sel:[0,1] op_sel_hi:[1,0]
	v_mov_b32_e32 v45, v32
	v_mov_b32_e32 v41, v33
	v_mov_b32_e32 v39, v35
	v_pk_add_f32 v[32:33], v[44:45], v[40:41]
	v_pk_add_f32 v[34:35], v[36:37], v[38:39]
	s_nop 0
	v_pk_add_f32 v[32:33], v[32:33], v[34:35]
	s_nop 0
	v_add_f32_e32 v32, v32, v33
	v_fmamk_f32 v32, v32, 0x3a000000, v111
	v_cmp_gt_f32_e64 s[74:75], s2, v32
	v_mul_f32_e32 v33, 0x4b800000, v32
	s_nop 0
	v_cndmask_b32_e64 v32, v32, v33, s[74:75]
	v_rsq_f32_e32 v32, v32
	s_nop 0
	v_mul_f32_e32 v33, 0x45800000, v32
	v_cndmask_b32_e64 v32, v32, v33, s[74:75]
	ds_write_b32 v98, v32

.Lmy_mix1_wdone:
	s_waitcnt vmcnt(0)
	s_waitcnt lgkmcnt(0)
	s_barrier
	s_lshl_b32 s78, s1, 1
	s_mov_b32 s79, s5
	v_or_b32_e32 v94, s90, v65
	v_or_b32_e32 v79, s4, v65
	v_ashrrev_i32_e32 v95, 31, v94
	v_lshlrev_b32_e32 v79, 2, v79
	v_lshlrev_b64 v[94:95], 12, v[94:95]
	s_add_i32 s93, s93, s0
	s_add_i32 s85, s85, s94
	ds_read_b64_tr_b16 v[180:181], v116
	ds_read_b64_tr_b16 v[182:183], v116 offset:2048
	ds_read_b128 v[132:135], v117
	ds_read_b128 v[136:139], v117 offset:8192
	ds_read_b128 v[140:143], v117 offset:16384
	ds_read_b128 v[144:147], v117 offset:24576
	ds_read_b64_tr_b16 v[184:185], v116 offset:8192
	ds_read_b64_tr_b16 v[186:187], v116 offset:10240
	ds_read_b128 v[148:151], v118
	ds_read_b128 v[152:155], v118 offset:8192
	ds_read_b128 v[156:159], v118 offset:16384
	ds_read_b128 v[160:163], v118 offset:24576
	s_waitcnt lgkmcnt(6)
	ds_read_b64_tr_b16 v[188:189], v116 offset:16384
	ds_read_b64_tr_b16 v[190:191], v116 offset:18432
	ds_read_b128 v[168:171], v119 offset:8192
	ds_read_b128 v[172:175], v119 offset:16384
	ds_read_b128 v[176:179], v119 offset:24576
	v_mfma_f32_32x32x16_bf16 v[48:63], v[180:183], v[132:135], 0
	v_mfma_f32_32x32x16_bf16 v[32:47], v[180:183], v[136:139], 0
	v_mfma_f32_32x32x16_bf16 v[16:31], v[180:183], v[140:143], 0
	v_mfma_f32_32x32x16_bf16 v[0:15], v[180:183], v[144:147], 0
	s_waitcnt lgkmcnt(5)
	ds_read_b64_tr_b16 v[180:181], v116 offset:24576
	ds_read_b64_tr_b16 v[182:183], v116 offset:26624
	ds_read_b128 v[136:139], v120 offset:8192
	ds_read_b128 v[140:143], v120 offset:16384
	ds_read_b128 v[144:147], v120 offset:24576
	v_mfma_f32_32x32x16_bf16 v[48:63], v[184:187], v[148:151], v[48:63]
	v_mfma_f32_32x32x16_bf16 v[32:47], v[184:187], v[152:155], v[32:47]
	v_mfma_f32_32x32x16_bf16 v[16:31], v[184:187], v[156:159], v[16:31]
	v_mfma_f32_32x32x16_bf16 v[0:15], v[184:187], v[160:163], v[0:15]
	s_waitcnt lgkmcnt(5)
	ds_read_b64_tr_b16 v[184:185], v116 offset:32768
	ds_read_b64_tr_b16 v[186:187], v116 offset:34816
	ds_read_b128 v[156:159], v121 offset:16384
	ds_read_b128 v[160:163], v121 offset:24576
	v_mfma_f32_32x32x16_bf16 v[32:47], v[188:191], v[168:171], v[32:47]
	v_mfma_f32_32x32x16_bf16 v[16:31], v[188:191], v[172:175], v[16:31]
	v_mfma_f32_32x32x16_bf16 v[0:15], v[188:191], v[176:179], v[0:15]
	s_waitcnt lgkmcnt(4)
	ds_read_b64_tr_b16 v[188:189], v116 offset:40960
	ds_read_b64_tr_b16 v[190:191], v116 offset:43008
	ds_read_b128 v[172:175], v122 offset:16384
	ds_read_b128 v[176:179], v122 offset:24576
	v_mfma_f32_32x32x16_bf16 v[32:47], v[180:183], v[136:139], v[32:47]
	v_mfma_f32_32x32x16_bf16 v[16:31], v[180:183], v[140:143], v[16:31]
	v_mfma_f32_32x32x16_bf16 v[0:15], v[180:183], v[144:147], v[0:15]
	s_waitcnt lgkmcnt(4)
	ds_read_b64_tr_b16 v[180:181], v116 offset:49152
	ds_read_b64_tr_b16 v[182:183], v116 offset:51200
	ds_read_b128 v[144:147], v123 offset:24576
	v_mfma_f32_32x32x16_bf16 v[16:31], v[184:187], v[156:159], v[16:31]
	v_mfma_f32_32x32x16_bf16 v[0:15], v[184:187], v[160:163], v[0:15]
	s_waitcnt lgkmcnt(3)
	ds_read_b64_tr_b16 v[184:185], v116 offset:57344
	ds_read_b64_tr_b16 v[186:187], v116 offset:59392
	ds_read_b128 v[160:163], v124 offset:24576
	v_mfma_f32_32x32x16_bf16 v[16:31], v[188:191], v[172:175], v[16:31]
	v_mfma_f32_32x32x16_bf16 v[0:15], v[188:191], v[176:179], v[0:15]
	s_waitcnt lgkmcnt(3)
	v_mfma_f32_32x32x16_bf16 v[0:15], v[180:183], v[144:147], v[0:15]
	s_waitcnt lgkmcnt(0)
	v_mfma_f32_32x32x16_bf16 v[0:15], v[184:187], v[160:163], v[0:15]
	v_lshl_add_u64 v[92:93], v[72:73], 0, s[78:79]
	s_lshl_b32 s78, s1, 2
	v_lshl_add_u64 v[90:91], v[74:75], 0, s[78:79]
	v_lshl_add_u64 v[94:95], v[92:93], 0, v[94:95]
	s_cmpk_gt_i32 s93, 0x3ff
	s_waitcnt vmcnt(0)
	v_fma_f32 v48, v48, v204, v200
	v_lshlrev_b32_e32 v132, 16, v220
	v_and_b32_e32 v133, 0xffff0000, v220
	v_fma_f32 v49, v49, v205, v200
	v_mul_f32_e32 v48, v48, v132
	v_mul_f32_e32 v49, v49, v133
	v_lshlrev_b32_e32 v134, 16, v221
	v_and_b32_e32 v135, 0xffff0000, v221
	v_fma_f32 v50, v50, v206, v200
	v_fma_f32 v51, v51, v207, v200
	v_mul_f32_e32 v50, v50, v134
	v_mul_f32_e32 v51, v51, v135
	v_cvt_pk_bf16_f32 v48, v48, v49
	v_cvt_pk_bf16_f32 v49, v50, v51
	global_store_dwordx2 v[192:193], v[48:49], off
	v_fma_f32 v52, v52, v208, v200
	v_lshlrev_b32_e32 v132, 16, v222
	v_and_b32_e32 v133, 0xffff0000, v222
	v_fma_f32 v53, v53, v209, v200
	v_mul_f32_e32 v52, v52, v132
	v_mul_f32_e32 v53, v53, v133
	v_lshlrev_b32_e32 v134, 16, v223
	v_and_b32_e32 v135, 0xffff0000, v223
	v_fma_f32 v54, v54, v210, v200
	v_fma_f32 v55, v55, v211, v200
	v_mul_f32_e32 v54, v54, v134
	v_mul_f32_e32 v55, v55, v135
	v_cvt_pk_bf16_f32 v52, v52, v53
	v_cvt_pk_bf16_f32 v53, v54, v55
	global_store_dwordx2 v[192:193], v[52:53], off offset:16
	v_fma_f32 v56, v56, v212, v200
	v_lshlrev_b32_e32 v132, 16, v224
	v_and_b32_e32 v133, 0xffff0000, v224
	v_fma_f32 v57, v57, v213, v200
	v_mul_f32_e32 v56, v56, v132
	v_mul_f32_e32 v57, v57, v133
	v_lshlrev_b32_e32 v134, 16, v225
	v_and_b32_e32 v135, 0xffff0000, v225
	v_fma_f32 v58, v58, v214, v200
	v_fma_f32 v59, v59, v215, v200
	v_mul_f32_e32 v58, v58, v134
	v_mul_f32_e32 v59, v59, v135
	v_cvt_pk_bf16_f32 v56, v56, v57
	v_cvt_pk_bf16_f32 v57, v58, v59
	global_store_dwordx2 v[192:193], v[56:57], off offset:32
	v_fma_f32 v60, v60, v216, v200
	v_lshlrev_b32_e32 v132, 16, v226
	v_and_b32_e32 v133, 0xffff0000, v226
	v_fma_f32 v61, v61, v217, v200
	v_mul_f32_e32 v60, v60, v132
	v_mul_f32_e32 v61, v61, v133
	v_lshlrev_b32_e32 v134, 16, v227
	v_and_b32_e32 v135, 0xffff0000, v227
	v_fma_f32 v62, v62, v218, v200
	v_fma_f32 v63, v63, v219, v200
	v_mul_f32_e32 v62, v62, v134
	v_mul_f32_e32 v63, v63, v135
	v_cvt_pk_bf16_f32 v60, v60, v61
	v_cvt_pk_bf16_f32 v61, v62, v63
	global_store_dwordx2 v[192:193], v[60:61], off offset:48
	v_fma_f32 v32, v32, v204, v201
	v_lshlrev_b32_e32 v132, 16, v228
	v_and_b32_e32 v133, 0xffff0000, v228
	v_fma_f32 v33, v33, v205, v201
	v_mul_f32_e32 v32, v32, v132
	v_mul_f32_e32 v33, v33, v133
	v_lshlrev_b32_e32 v134, 16, v229
	v_and_b32_e32 v135, 0xffff0000, v229
	v_fma_f32 v34, v34, v206, v201
	v_fma_f32 v35, v35, v207, v201
	v_mul_f32_e32 v34, v34, v134
	v_mul_f32_e32 v35, v35, v135
	v_cvt_pk_bf16_f32 v32, v32, v33
	v_cvt_pk_bf16_f32 v33, v34, v35
	global_store_dwordx2 v[194:195], v[32:33], off
	v_fma_f32 v36, v36, v208, v201
	v_lshlrev_b32_e32 v132, 16, v230
	v_and_b32_e32 v133, 0xffff0000, v230
	v_fma_f32 v37, v37, v209, v201
	v_mul_f32_e32 v36, v36, v132
	v_mul_f32_e32 v37, v37, v133
	v_lshlrev_b32_e32 v134, 16, v231
	v_and_b32_e32 v135, 0xffff0000, v231
	v_fma_f32 v38, v38, v210, v201
	v_fma_f32 v39, v39, v211, v201
	v_mul_f32_e32 v38, v38, v134
	v_mul_f32_e32 v39, v39, v135
	v_cvt_pk_bf16_f32 v36, v36, v37
	v_cvt_pk_bf16_f32 v37, v38, v39
	global_store_dwordx2 v[194:195], v[36:37], off offset:16
	v_fma_f32 v40, v40, v212, v201
	v_lshlrev_b32_e32 v132, 16, v232
	v_and_b32_e32 v133, 0xffff0000, v232
	v_fma_f32 v41, v41, v213, v201
	v_mul_f32_e32 v40, v40, v132
	v_mul_f32_e32 v41, v41, v133
	v_lshlrev_b32_e32 v134, 16, v233
	v_and_b32_e32 v135, 0xffff0000, v233
	v_fma_f32 v42, v42, v214, v201
	v_fma_f32 v43, v43, v215, v201
	v_mul_f32_e32 v42, v42, v134
	v_mul_f32_e32 v43, v43, v135
	v_cvt_pk_bf16_f32 v40, v40, v41
	v_cvt_pk_bf16_f32 v41, v42, v43
	global_store_dwordx2 v[194:195], v[40:41], off offset:32
	v_fma_f32 v44, v44, v216, v201
	v_lshlrev_b32_e32 v132, 16, v234
	v_and_b32_e32 v133, 0xffff0000, v234
	v_fma_f32 v45, v45, v217, v201
	v_mul_f32_e32 v44, v44, v132
	v_mul_f32_e32 v45, v45, v133
	v_lshlrev_b32_e32 v134, 16, v235
	v_and_b32_e32 v135, 0xffff0000, v235
	v_fma_f32 v46, v46, v218, v201
	v_fma_f32 v47, v47, v219, v201
	v_mul_f32_e32 v46, v46, v134
	v_mul_f32_e32 v47, v47, v135
	v_cvt_pk_bf16_f32 v44, v44, v45
	v_cvt_pk_bf16_f32 v45, v46, v47
	global_store_dwordx2 v[194:195], v[44:45], off offset:48
	v_fma_f32 v16, v16, v204, v202
	v_lshlrev_b32_e32 v132, 16, v236
	v_and_b32_e32 v133, 0xffff0000, v236
	v_fma_f32 v17, v17, v205, v202
	v_mul_f32_e32 v16, v16, v132
	v_mul_f32_e32 v17, v17, v133
	v_lshlrev_b32_e32 v134, 16, v237
	v_and_b32_e32 v135, 0xffff0000, v237
	v_fma_f32 v18, v18, v206, v202
	v_fma_f32 v19, v19, v207, v202
	v_mul_f32_e32 v18, v18, v134
	v_mul_f32_e32 v19, v19, v135
	v_cvt_pk_bf16_f32 v16, v16, v17
	v_cvt_pk_bf16_f32 v17, v18, v19
	global_store_dwordx2 v[196:197], v[16:17], off
	v_fma_f32 v20, v20, v208, v202
	v_lshlrev_b32_e32 v132, 16, v238
	v_and_b32_e32 v133, 0xffff0000, v238
	v_fma_f32 v21, v21, v209, v202
	v_mul_f32_e32 v20, v20, v132
	v_mul_f32_e32 v21, v21, v133
	v_lshlrev_b32_e32 v134, 16, v239
	v_and_b32_e32 v135, 0xffff0000, v239
	v_fma_f32 v22, v22, v210, v202
	v_fma_f32 v23, v23, v211, v202
	v_mul_f32_e32 v22, v22, v134
	v_mul_f32_e32 v23, v23, v135
	v_cvt_pk_bf16_f32 v20, v20, v21
	v_cvt_pk_bf16_f32 v21, v22, v23
	global_store_dwordx2 v[196:197], v[20:21], off offset:16
	v_fma_f32 v24, v24, v212, v202
	v_lshlrev_b32_e32 v132, 16, v240
	v_and_b32_e32 v133, 0xffff0000, v240
	v_fma_f32 v25, v25, v213, v202
	v_mul_f32_e32 v24, v24, v132
	v_mul_f32_e32 v25, v25, v133
	v_lshlrev_b32_e32 v134, 16, v241
	v_and_b32_e32 v135, 0xffff0000, v241
	v_fma_f32 v26, v26, v214, v202
	v_fma_f32 v27, v27, v215, v202
	v_mul_f32_e32 v26, v26, v134
	v_mul_f32_e32 v27, v27, v135
	v_cvt_pk_bf16_f32 v24, v24, v25
	v_cvt_pk_bf16_f32 v25, v26, v27
	global_store_dwordx2 v[196:197], v[24:25], off offset:32
	v_fma_f32 v28, v28, v216, v202
	v_lshlrev_b32_e32 v132, 16, v242
	v_and_b32_e32 v133, 0xffff0000, v242
	v_fma_f32 v29, v29, v217, v202
	v_mul_f32_e32 v28, v28, v132
	v_mul_f32_e32 v29, v29, v133
	v_lshlrev_b32_e32 v134, 16, v243
	v_and_b32_e32 v135, 0xffff0000, v243
	v_fma_f32 v30, v30, v218, v202
	v_fma_f32 v31, v31, v219, v202
	v_mul_f32_e32 v30, v30, v134
	v_mul_f32_e32 v31, v31, v135
	v_cvt_pk_bf16_f32 v28, v28, v29
	v_cvt_pk_bf16_f32 v29, v30, v31
	global_store_dwordx2 v[196:197], v[28:29], off offset:48
	v_fma_f32 v0, v0, v204, v203
	v_lshlrev_b32_e32 v132, 16, v244
	v_and_b32_e32 v133, 0xffff0000, v244
	v_fma_f32 v1, v1, v205, v203
	v_mul_f32_e32 v0, v0, v132
	v_mul_f32_e32 v1, v1, v133
	v_lshlrev_b32_e32 v134, 16, v245
	v_and_b32_e32 v135, 0xffff0000, v245
	v_fma_f32 v2, v2, v206, v203
	v_fma_f32 v3, v3, v207, v203
	v_mul_f32_e32 v2, v2, v134
	v_mul_f32_e32 v3, v3, v135
	v_cvt_pk_bf16_f32 v0, v0, v1
	v_cvt_pk_bf16_f32 v1, v2, v3
	global_store_dwordx2 v[198:199], v[0:1], off
	v_fma_f32 v4, v4, v208, v203
	v_lshlrev_b32_e32 v132, 16, v246
	v_and_b32_e32 v133, 0xffff0000, v246
	v_fma_f32 v5, v5, v209, v203
	v_mul_f32_e32 v4, v4, v132
	v_mul_f32_e32 v5, v5, v133
	v_lshlrev_b32_e32 v134, 16, v247
	v_and_b32_e32 v135, 0xffff0000, v247
	v_fma_f32 v6, v6, v210, v203
	v_fma_f32 v7, v7, v211, v203
	v_mul_f32_e32 v6, v6, v134
	v_mul_f32_e32 v7, v7, v135
	v_cvt_pk_bf16_f32 v4, v4, v5
	v_cvt_pk_bf16_f32 v5, v6, v7
	global_store_dwordx2 v[198:199], v[4:5], off offset:16
	v_fma_f32 v8, v8, v212, v203
	v_lshlrev_b32_e32 v132, 16, v248
	v_and_b32_e32 v133, 0xffff0000, v248
	v_fma_f32 v9, v9, v213, v203
	v_mul_f32_e32 v8, v8, v132
	v_mul_f32_e32 v9, v9, v133
	v_lshlrev_b32_e32 v134, 16, v249
	v_and_b32_e32 v135, 0xffff0000, v249
	v_fma_f32 v10, v10, v214, v203
	v_fma_f32 v11, v11, v215, v203
	v_mul_f32_e32 v10, v10, v134
	v_mul_f32_e32 v11, v11, v135
	v_cvt_pk_bf16_f32 v8, v8, v9
	v_cvt_pk_bf16_f32 v9, v10, v11
	global_store_dwordx2 v[198:199], v[8:9], off offset:32
	v_fma_f32 v12, v12, v216, v203
	v_lshlrev_b32_e32 v132, 16, v250
	v_and_b32_e32 v133, 0xffff0000, v250
	v_fma_f32 v13, v13, v217, v203
	v_mul_f32_e32 v12, v12, v132
	v_mul_f32_e32 v13, v13, v133
	v_lshlrev_b32_e32 v134, 16, v251
	v_and_b32_e32 v135, 0xffff0000, v251
	v_fma_f32 v14, v14, v218, v203
	v_fma_f32 v15, v15, v219, v203
	v_mul_f32_e32 v14, v14, v134
	v_mul_f32_e32 v15, v15, v135
	v_cvt_pk_bf16_f32 v12, v12, v13
	v_cvt_pk_bf16_f32 v13, v14, v15
	global_store_dwordx2 v[198:199], v[12:13], off offset:48
	s_barrier
	s_cbranch_scc1 .LBB0_1061
.LBB0_995:
	s_and_b32 s1, s93, 7
	s_and_b32 s90, s85, 0xffffff80
	s_lshl_b32 s2, s1, 9
	v_readlane_b32 s4, v255, 35
	v_add_u32_e32 v0, s90, v100
	s_add_u32 s78, s4, s2
	v_readlane_b32 s2, v255, 37
	v_ashrrev_i32_e32 v1, 31, v0
	s_addc_u32 s79, s2, 0
	v_lshlrev_b64 v[0:1], 12, v[0:1]
	v_lshl_add_u64 v[0:1], s[78:79], 0, v[0:1]
	s_mov_b32 m0, s95
	v_lshl_add_u64 v[0:1], v[0:1], 0, v[76:77]
	global_load_lds_dwordx4 v[0:1], off
	v_add_u32_e32 v0, s90, v101
	v_ashrrev_i32_e32 v1, 31, v0
	v_lshlrev_b64 v[0:1], 12, v[0:1]
	v_lshl_add_u64 v[0:1], s[78:79], 0, v[0:1]
	v_lshl_add_u64 v[0:1], v[0:1], 0, v[66:67]
	s_mov_b32 m0, s10
	v_mov_b32_e32 v79, v67
	global_load_lds_dwordx4 v[0:1], off
	v_add_u32_e32 v0, s90, v102
	v_ashrrev_i32_e32 v1, 31, v0
	v_lshlrev_b64 v[0:1], 12, v[0:1]
	v_lshl_add_u64 v[0:1], s[78:79], 0, v[0:1]
	v_lshl_add_u64 v[0:1], v[0:1], 0, v[78:79]
	s_mov_b32 m0, s11
	v_mov_b32_e32 v81, v67
	global_load_lds_dwordx4 v[0:1], off
	v_add_u32_e32 v0, s90, v103
	v_ashrrev_i32_e32 v1, 31, v0
	v_lshlrev_b64 v[0:1], 12, v[0:1]
	v_lshl_add_u64 v[0:1], s[78:79], 0, v[0:1]
	v_lshl_add_u64 v[0:1], v[0:1], 0, v[80:81]
	s_mov_b32 m0, s86
	v_mov_b32_e32 v83, v67
	global_load_lds_dwordx4 v[0:1], off
	v_add_u32_e32 v0, s90, v104
	v_ashrrev_i32_e32 v1, 31, v0
	v_lshlrev_b64 v[0:1], 12, v[0:1]
	v_lshl_add_u64 v[0:1], s[78:79], 0, v[0:1]
	v_lshl_add_u64 v[0:1], v[0:1], 0, v[82:83]
	s_mov_b32 m0, s87
	v_mov_b32_e32 v85, v67
	global_load_lds_dwordx4 v[0:1], off
	v_add_u32_e32 v0, s90, v105
	v_ashrrev_i32_e32 v1, 31, v0
	v_lshlrev_b64 v[0:1], 12, v[0:1]
	v_lshl_add_u64 v[0:1], s[78:79], 0, v[0:1]
	v_lshl_add_u64 v[0:1], v[0:1], 0, v[84:85]
	s_mov_b32 m0, s6
	v_mov_b32_e32 v87, v67
	global_load_lds_dwordx4 v[0:1], off
	v_add_u32_e32 v0, s90, v106
	v_ashrrev_i32_e32 v1, 31, v0
	v_lshlrev_b64 v[0:1], 12, v[0:1]
	v_lshl_add_u64 v[0:1], s[78:79], 0, v[0:1]
	v_lshl_add_u64 v[0:1], v[0:1], 0, v[86:87]
	s_mov_b32 m0, s7
	v_mov_b32_e32 v89, v67
	global_load_lds_dwordx4 v[0:1], off
	v_add_u32_e32 v0, s90, v107
	v_ashrrev_i32_e32 v1, 31, v0
	v_lshlrev_b64 v[0:1], 12, v[0:1]
	v_lshl_add_u64 v[0:1], s[78:79], 0, v[0:1]
	v_lshl_add_u64 v[0:1], v[0:1], 0, v[88:89]
	s_mov_b32 m0, s92
	s_nop 0
	global_load_lds_dwordx4 v[0:1], off
	s_lshl_b32 s98, s1, 9
	s_mov_b32 s99, 0
	v_lshl_add_u64 v[2:3], v[72:73], 0, s[98:99]
	s_lshl_b32 s98, s1, 10
	v_lshl_add_u64 v[4:5], v[74:75], 0, s[98:99]
	s_lshl_b32 s98, s1, 7
	v_or_b32_e32 v6, s90, v65
	v_ashrrev_i32_e32 v7, 31, v6
	v_lshlrev_b64 v[6:7], 12, v[6:7]
	v_lshl_add_u64 v[192:193], v[2:3], 0, v[6:7]
	v_or_b32_e32 v6, s98, v65
	v_lshlrev_b32_e32 v6, 2, v6
	global_load_dword v200, v6, s[8:9]
	global_load_dwordx2 v[220:221], v[192:193], off
	global_load_dwordx2 v[222:223], v[192:193], off offset:16
	global_load_dwordx2 v[224:225], v[192:193], off offset:32
	global_load_dwordx2 v[226:227], v[192:193], off offset:48
	v_or_b32_e32 v6, s90, v108
	v_ashrrev_i32_e32 v7, 31, v6
	v_lshlrev_b64 v[6:7], 12, v[6:7]
	v_lshl_add_u64 v[194:195], v[2:3], 0, v[6:7]
	v_or_b32_e32 v6, s98, v108
	v_lshlrev_b32_e32 v6, 2, v6
	global_load_dword v201, v6, s[8:9]
	global_load_dwordx2 v[228:229], v[194:195], off
	global_load_dwordx2 v[230:231], v[194:195], off offset:16
	global_load_dwordx2 v[232:233], v[194:195], off offset:32
	global_load_dwordx2 v[234:235], v[194:195], off offset:48
	v_or_b32_e32 v6, s90, v109
	v_ashrrev_i32_e32 v7, 31, v6
	v_lshlrev_b64 v[6:7], 12, v[6:7]
	v_lshl_add_u64 v[196:197], v[2:3], 0, v[6:7]
	v_or_b32_e32 v6, s98, v109
	v_lshlrev_b32_e32 v6, 2, v6
	global_load_dword v202, v6, s[8:9]
	global_load_dwordx2 v[236:237], v[196:197], off
	global_load_dwordx2 v[238:239], v[196:197], off offset:16
	global_load_dwordx2 v[240:241], v[196:197], off offset:32
	global_load_dwordx2 v[242:243], v[196:197], off offset:48
	v_or_b32_e32 v6, s90, v110
	v_ashrrev_i32_e32 v7, 31, v6
	v_lshlrev_b64 v[6:7], 12, v[6:7]
	v_lshl_add_u64 v[198:199], v[2:3], 0, v[6:7]
	v_or_b32_e32 v6, s98, v110
	v_lshlrev_b32_e32 v6, 2, v6
	global_load_dword v203, v6, s[8:9]
	global_load_dwordx2 v[244:245], v[198:199], off
	global_load_dwordx2 v[246:247], v[198:199], off offset:16
	global_load_dwordx2 v[248:249], v[198:199], off offset:32
	global_load_dwordx2 v[250:251], v[198:199], off offset:48
	global_load_dwordx4 v[204:207], v[4:5], off
	global_load_dwordx4 v[208:211], v[4:5], off offset:32
	global_load_dwordx4 v[212:215], v[4:5], off offset:64
	global_load_dwordx4 v[216:219], v[4:5], off offset:96
	s_and_saveexec_b64 s[96:97], vcc
	s_cbranch_execz .LBB0_997
	v_add_u32_e32 v0, s90, v96
	v_ashrrev_i32_e32 v1, 31, v0
	v_readlane_b32 s78, v255, 22
	v_lshlrev_b64 v[0:1], 7, v[0:1]
	v_readlane_b32 s79, v255, 23
	s_mov_b32 s2, 0x800000
	s_nop 0
	v_lshl_add_u64 v[16:17], s[78:79], 0, v[0:1]
	global_load_dwordx4 v[0:3], v[16:17], off offset:48
	global_load_dwordx4 v[4:7], v[16:17], off offset:32
	global_load_dwordx4 v[8:11], v[16:17], off
	global_load_dwordx4 v[12:15], v[16:17], off offset:16
	global_load_dwordx4 v[32:35], v[16:17], off offset:112
	global_load_dwordx4 v[36:39], v[16:17], off offset:96
	global_load_dwordx4 v[40:43], v[16:17], off offset:80
	global_load_dwordx4 v[44:47], v[16:17], off offset:64
	s_waitcnt vmcnt(0)
	v_add_f32_e32 v22, v0, v1
	v_add_f32_e32 v24, v2, v3
	v_mov_b32_e32 v18, v8
	v_mov_b32_e32 v19, v12
	v_mov_b32_e32 v12, v9
	v_pk_add_f32 v[8:9], v[18:19], v[12:13]
	v_mov_b32_e32 v12, v10
	v_mov_b32_e32 v13, v14
	v_mov_b32_e32 v14, v11
	v_pk_add_f32 v[10:11], v[12:13], v[14:15]
	s_nop 0
	v_pk_add_f32 v[8:9], v[8:9], v[10:11]
	s_nop 0
	v_add_f32_e32 v8, 0, v8
	v_add_f32_e32 v18, v8, v9
	v_mov_b32_e32 v8, v5
	v_mov_b32_e32 v9, v6
	v_mov_b32_e32 v5, v7
	v_pk_add_f32 v[4:5], v[8:9], v[4:5]
	s_nop 0
	v_pk_add_f32 v[20:21], v[4:5], v[4:5] op_sel:[0,1] op_sel_hi:[1,0]
	v_add_f32_e32 v36, v36, v37
	v_add_f32_e32 v38, v38, v39
	v_mov_b32_e32 v19, v44
	v_mov_b32_e32 v21, v45
	v_mov_b32_e32 v23, v46
	v_mov_b32_e32 v25, v47
	v_pk_add_f32 v[44:45], v[18:19], v[20:21]
	v_pk_add_f32 v[46:47], v[22:23], v[24:25]
	v_mov_b32_e32 v37, v34
	v_pk_add_f32 v[44:45], v[44:45], v[46:47]
	v_mov_b32_e32 v46, v41
	v_mov_b32_e32 v47, v42
	v_mov_b32_e32 v41, v43
	v_pk_add_f32 v[40:41], v[46:47], v[40:41]
	v_pk_add_f32 v[44:45], v[44:45], v[44:45] op_sel:[0,1] op_sel_hi:[1,0]
	v_pk_add_f32 v[40:41], v[40:41], v[40:41] op_sel:[0,1] op_sel_hi:[1,0]
	v_mov_b32_e32 v45, v32
	v_mov_b32_e32 v41, v33
	v_mov_b32_e32 v39, v35
	v_pk_add_f32 v[32:33], v[44:45], v[40:41]
	v_pk_add_f32 v[34:35], v[36:37], v[38:39]
	s_nop 0
	v_pk_add_f32 v[32:33], v[32:33], v[34:35]
	s_nop 0
	v_add_f32_e32 v32, v32, v33
	v_fmamk_f32 v32, v32, 0x3a000000, v111
	v_cmp_gt_f32_e64 s[78:79], s2, v32
	v_mul_f32_e32 v33, 0x4b800000, v32
	s_nop 0
	v_cndmask_b32_e64 v32, v32, v33, s[78:79]
	v_rsq_f32_e32 v32, v32
	s_nop 0
	v_mul_f32_e32 v33, 0x45800000, v32
	v_cndmask_b32_e64 v32, v32, v33, s[78:79]
	ds_write_b32 v98, v32

	.amdhsa_kernel _Z10fwd_kernel4Args
		.amdhsa_group_segment_fixed_size 0
		.amdhsa_private_segment_fixed_size 0
		.amdhsa_kernarg_size 472
		.amdhsa_user_sgpr_count 2
		.amdhsa_user_sgpr_dispatch_ptr 0
		.amdhsa_user_sgpr_queue_ptr 0
		.amdhsa_user_sgpr_kernarg_segment_ptr 1
		.amdhsa_user_sgpr_dispatch_id 0
		.amdhsa_user_sgpr_kernarg_preload_length 0
		.amdhsa_user_sgpr_kernarg_preload_offset 0
		.amdhsa_user_sgpr_private_segment_size 0
		.amdhsa_uses_dynamic_stack 0
		.amdhsa_enable_private_segment 0
		.amdhsa_system_sgpr_workgroup_id_x 1
		.amdhsa_system_sgpr_workgroup_id_y 0
		.amdhsa_system_sgpr_workgroup_id_z 0
		.amdhsa_system_sgpr_workgroup_info 0
		.amdhsa_system_vgpr_workitem_id 0
		.amdhsa_next_free_vgpr 256
		.amdhsa_next_free_sgpr 100
		.amdhsa_accum_offset 256
		.amdhsa_reserve_vcc 1
		.amdhsa_float_round_mode_32 0
		.amdhsa_float_round_mode_16_64 0
		.amdhsa_float_denorm_mode_32 3
		.amdhsa_float_denorm_mode_16_64 3
		.amdhsa_dx10_clamp 1
		.amdhsa_ieee_mode 1
		.amdhsa_fp16_overflow 0
		.amdhsa_tg_split 0
		.amdhsa_exception_fp_ieee_invalid_op 0
		.amdhsa_exception_fp_denorm_src 0
		.amdhsa_exception_fp_ieee_div_zero 0
		.amdhsa_exception_fp_ieee_overflow 0
		.amdhsa_exception_fp_ieee_underflow 0
		.amdhsa_exception_fp_ieee_inexact 0
		.amdhsa_exception_int_div_zero 0
	.end_amdhsa_kernel

amdhsa.kernels:
  - .agpr_count:     0
    .args:
      - .offset:         0
        .size:           216
        .value_kind:     by_value
      - .offset:         216
        .size:           4
        .value_kind:     hidden_block_count_x
      - .offset:         220
        .size:           4
        .value_kind:     hidden_block_count_y
      - .offset:         224
        .size:           4
        .value_kind:     hidden_block_count_z
      - .offset:         228
        .size:           2
        .value_kind:     hidden_group_size_x
      - .offset:         230
        .size:           2
        .value_kind:     hidden_group_size_y
      - .offset:         232
        .size:           2
        .value_kind:     hidden_group_size_z
      - .offset:         234
        .size:           2
        .value_kind:     hidden_remainder_x
      - .offset:         236
        .size:           2
        .value_kind:     hidden_remainder_y
      - .offset:         238
        .size:           2
        .value_kind:     hidden_remainder_z
      - .offset:         256
        .size:           8
        .value_kind:     hidden_global_offset_x
      - .offset:         264
        .size:           8
        .value_kind:     hidden_global_offset_y
      - .offset:         272
        .size:           8
        .value_kind:     hidden_global_offset_z
      - .offset:         280
        .size:           2
        .value_kind:     hidden_grid_dims
      - .offset:         336
        .size:           4
        .value_kind:     hidden_dynamic_lds_size
    .group_segment_fixed_size: 0
    .kernarg_segment_align: 8
    .kernarg_segment_size: 472
    .language:       OpenCL C
    .language_version:
      - 2
      - 0
    .max_flat_workgroup_size: 512
    .name:           _Z10fwd_kernel4Args
    .private_segment_fixed_size: 0
    .sgpr_count:     106
    .sgpr_spill_count: 129
    .symbol:         _Z10fwd_kernel4Args.kd
    .uniform_work_group_size: 1
    .uses_dynamic_stack: false
    .vgpr_count:     256
    .vgpr_spill_count: 0
    .wavefront_size: 64
